# v15 + DIFF combine loop: second row's three loads issued together with the first row's (counted waits)
# speedup vs baseline: 1.0097x; 1.0059x over previous
.LBB0_709:
	v_lshl_add_u64 v[2:3], v[24:25], 0, v[0:1]
	v_add_co_u32_e32 v28, vcc, 0x27a0000, v2
	v_lshl_add_u64 v[32:33], v[22:23], 0, v[0:1]
	s_nop 0
	v_addc_co_u32_e32 v29, vcc, 0, v3, vcc
	global_load_dwordx4 v[2:5], v[28:29], off
	s_nop 0
	global_load_dwordx4 v[28:31], v[28:29], off offset:256
	s_mov_b32 s4, 0x27a2000
	global_load_dwordx4 v[32:35], v[32:33], off
	s_mov_b64 s[100:101], 0x27a2000
	v_lshl_add_u64 v[204:205], v[18:19], 0, v[0:1]
	v_lshl_add_u64 v[206:207], v[16:17], 0, v[0:1]
	v_lshl_add_u64 v[204:205], v[204:205], 0, s[100:101]
	global_load_dwordx4 v[192:195], v[204:205], off
	global_load_dwordx4 v[196:199], v[204:205], off offset:256
	global_load_dwordx4 v[200:203], v[206:207], off
	s_add_i32 s6, s6, -2
	v_lshl_add_u64 v[22:23], v[22:23], 0, s[24:25]
	v_lshl_add_u64 v[24:25], v[24:25], 0, s[42:43]
	s_cmp_lg_u32 s6, 0
	s_waitcnt vmcnt(5)
	v_lshlrev_b32_e32 v36, 16, v5
	v_and_b32_e32 v37, 0xffff0000, v5
	s_waitcnt vmcnt(4)
	v_lshlrev_b32_e32 v38, 16, v31
	v_and_b32_e32 v39, 0xffff0000, v31
	v_pk_fma_f32 v[36:37], v[6:7], v[38:39], v[36:37] neg_lo:[1,0,0] neg_hi:[1,0,0]
	v_lshlrev_b32_e32 v38, 16, v4
	v_and_b32_e32 v39, 0xffff0000, v4
	v_lshlrev_b32_e32 v4, 16, v30
	v_and_b32_e32 v5, 0xffff0000, v30
	v_pk_fma_f32 v[4:5], v[6:7], v[4:5], v[38:39] neg_lo:[1,0,0] neg_hi:[1,0,0]
	v_mov_b32_e32 v30, v36
	v_mov_b32_e32 v31, v4
	v_pk_mul_f32 v[30:31], v[30:31], v[30:31]
	v_mov_b32_e32 v38, v37
	v_mov_b32_e32 v39, v5
	v_pk_fma_f32 v[30:31], v[38:39], v[38:39], v[30:31]
	s_waitcnt vmcnt(3)
	v_lshlrev_b32_e32 v38, 16, v34
	v_and_b32_e32 v39, 0xffff0000, v34
	v_mul_f32_e32 v34, 0xbfb8aa3b, v38
	v_exp_f32_e32 v34, v34
	v_lshlrev_b32_e32 v42, 16, v29
	v_and_b32_e32 v43, 0xffff0000, v29
	v_add_f32_e32 v34, 1.0, v34
	v_rcp_f32_e32 v40, v34
	v_mul_f32_e32 v34, 0xbfb8aa3b, v39
	v_exp_f32_e32 v34, v34
	s_nop 0
	v_add_f32_e32 v34, 1.0, v34
	v_rcp_f32_e32 v41, v34
	s_nop 0
	v_pk_mul_f32 v[38:39], v[40:41], v[38:39]
	v_lshlrev_b32_e32 v40, 16, v3
	v_and_b32_e32 v41, 0xffff0000, v3
	v_pk_fma_f32 v[40:41], v[6:7], v[42:43], v[40:41] neg_lo:[1,0,0] neg_hi:[1,0,0]
	v_lshlrev_b32_e32 v42, 16, v33
	v_mul_f32_e32 v3, 0xbfb8aa3b, v42
	v_exp_f32_e32 v3, v3
	v_and_b32_e32 v43, 0xffff0000, v33
	v_mov_b32_e32 v29, v40
	v_add_f32_e32 v3, 1.0, v3
	v_rcp_f32_e32 v44, v3
	v_mul_f32_e32 v3, 0xbfb8aa3b, v43
	v_exp_f32_e32 v3, v3
	s_nop 0
	v_add_f32_e32 v3, 1.0, v3
	v_rcp_f32_e32 v45, v3
	v_and_b32_e32 v3, 0xffff0000, v28
	v_pk_mul_f32 v[42:43], v[44:45], v[42:43]
	v_lshlrev_b32_e32 v44, 16, v2
	v_and_b32_e32 v45, 0xffff0000, v2
	v_lshlrev_b32_e32 v2, 16, v28
	v_pk_fma_f32 v[2:3], v[6:7], v[2:3], v[44:45] neg_lo:[1,0,0] neg_hi:[1,0,0]
	v_mov_b32_e32 v45, v41
	v_mov_b32_e32 v28, v2
	v_pk_mul_f32 v[28:29], v[28:29], v[28:29]
	v_mov_b32_e32 v44, v3
	v_pk_fma_f32 v[28:29], v[44:45], v[44:45], v[28:29]
	v_lshlrev_b32_e32 v44, 16, v32
	v_add_f32_e32 v28, v28, v29
	v_add_f32_e32 v28, v31, v28
	v_add_f32_e32 v28, v30, v28
	v_and_b32_e32 v45, 0xffff0000, v32
	v_mul_f32_e32 v32, 0xbfb8aa3b, v44
	v_add_f32_dpp v28, v28, v28 quad_perm:[1,0,3,2] row_mask:0xf bank_mask:0xf bound_ctrl:1
	v_mul_f32_e32 v33, 0xbfb8aa3b, v45
	v_exp_f32_e32 v32, v32
	v_add_f32_dpp v28, v28, v28 quad_perm:[2,3,0,1] row_mask:0xf bank_mask:0xf bound_ctrl:1
	v_exp_f32_e32 v33, v33
	v_add_f32_e32 v32, 1.0, v32
	v_add_f32_dpp v28, v28, v28 row_half_mirror row_mask:0xf bank_mask:0xf bound_ctrl:1
	v_add_f32_e32 v33, 1.0, v33
	v_rcp_f32_e32 v32, v32
	v_add_f32_dpp v28, v28, v28 row_mirror row_mask:0xf bank_mask:0xf bound_ctrl:1
	v_fmamk_f32 v28, v28, 0x3c000000, v245
	v_cmp_gt_f32_e32 vcc, s75, v28
	v_mul_f32_e32 v29, 0x4b800000, v28
	v_rcp_f32_e32 v33, v33
	v_cndmask_b32_e32 v28, v28, v29, vcc
	v_rsq_f32_e32 v28, v28
	v_pk_mul_f32 v[32:33], v[32:33], v[44:45]
	v_mul_f32_e32 v29, 0x45800000, v28
	v_cndmask_b32_e32 v28, v28, v29, vcc
	v_pk_mul_f32 v[2:3], v[2:3], v[28:29] op_sel_hi:[1,0]
	v_pk_mul_f32 v[30:31], v[40:41], v[28:29] op_sel_hi:[1,0]
	v_pk_mul_f32 v[2:3], v[8:9], v[2:3]
	v_pk_mul_f32 v[30:31], v[10:11], v[30:31]
	v_pk_mul_f32 v[4:5], v[4:5], v[28:29] op_sel_hi:[1,0]
	v_pk_mul_f32 v[2:3], v[32:33], v[2:3]
	v_pk_mul_f32 v[30:31], v[42:43], v[30:31]
	v_pk_mul_f32 v[4:5], v[12:13], v[4:5]
	v_cvt_pk_bf16_f32 v2, v2, v3
	v_cvt_pk_bf16_f32 v3, v30, v31
	v_pk_mul_f32 v[4:5], v[38:39], v[4:5]
	v_lshlrev_b32_e32 v30, 16, v35
	v_cvt_pk_bf16_f32 v4, v4, v5
	v_mul_f32_e32 v5, 0xbfb8aa3b, v30
	v_exp_f32_e32 v5, v5
	v_and_b32_e32 v31, 0xffff0000, v35
	v_pk_mul_f32 v[28:29], v[36:37], v[28:29] op_sel_hi:[1,0]
	v_add_f32_e32 v5, 1.0, v5
	v_rcp_f32_e32 v32, v5
	v_mul_f32_e32 v5, 0xbfb8aa3b, v31
	v_exp_f32_e32 v5, v5
	v_pk_mul_f32 v[28:29], v[14:15], v[28:29]
	v_add_f32_e32 v5, 1.0, v5
	v_rcp_f32_e32 v33, v5
	s_nop 0
	v_pk_mul_f32 v[30:31], v[32:33], v[30:31]
	s_nop 0
	v_pk_mul_f32 v[28:29], v[30:31], v[28:29]
	v_lshl_add_u64 v[32:33], v[16:17], 0, v[0:1]
	v_cvt_pk_bf16_f32 v5, v28, v29
	v_lshl_add_u64 v[28:29], v[26:27], 0, v[0:1]
	global_store_dwordx4 v[28:29], v[2:5], off
	v_lshl_add_u64 v[16:17], v[16:17], 0, s[24:25]
	v_lshl_add_u64 v[26:27], v[26:27], 0, s[42:43]
	v_lshl_add_u64 v[2:3], v[18:19], 0, v[0:1]
	v_add_co_u32_e32 v28, vcc, s4, v2
	v_lshl_add_u64 v[18:19], v[18:19], 0, s[42:43]
	s_nop 0
	v_addc_co_u32_e32 v29, vcc, 0, v3, vcc
	s_waitcnt vmcnt(1)
	v_mov_b32_e32 v2, v192
	v_mov_b32_e32 v3, v193
	v_mov_b32_e32 v4, v194
	v_mov_b32_e32 v5, v195
	s_nop 0
	v_mov_b32_e32 v28, v196
	v_mov_b32_e32 v29, v197
	v_mov_b32_e32 v30, v198
	v_mov_b32_e32 v31, v199
	s_waitcnt vmcnt(1)
	v_lshlrev_b32_e32 v36, 16, v5
	v_mov_b32_e32 v32, v200
	v_mov_b32_e32 v33, v201
	v_mov_b32_e32 v34, v202
	v_mov_b32_e32 v35, v203
	v_and_b32_e32 v37, 0xffff0000, v5
	s_waitcnt vmcnt(1)
	v_lshlrev_b32_e32 v38, 16, v31
	v_and_b32_e32 v39, 0xffff0000, v31
	v_pk_fma_f32 v[36:37], v[6:7], v[38:39], v[36:37] neg_lo:[1,0,0] neg_hi:[1,0,0]
	v_lshlrev_b32_e32 v38, 16, v4
	v_and_b32_e32 v39, 0xffff0000, v4
	v_lshlrev_b32_e32 v4, 16, v30
	v_and_b32_e32 v5, 0xffff0000, v30
	v_pk_fma_f32 v[4:5], v[6:7], v[4:5], v[38:39] neg_lo:[1,0,0] neg_hi:[1,0,0]
	v_mov_b32_e32 v30, v36
	v_mov_b32_e32 v31, v4
	v_pk_mul_f32 v[30:31], v[30:31], v[30:31]
	v_mov_b32_e32 v38, v37
	v_mov_b32_e32 v39, v5
	v_pk_fma_f32 v[30:31], v[38:39], v[38:39], v[30:31]
	v_lshlrev_b32_e32 v42, 16, v29
	v_and_b32_e32 v43, 0xffff0000, v29
	s_nop 0
	v_lshlrev_b32_e32 v38, 16, v34
	v_and_b32_e32 v39, 0xffff0000, v34
	v_mul_f32_e32 v34, 0xbfb8aa3b, v38
	v_exp_f32_e32 v34, v34
	s_nop 0
	v_add_f32_e32 v34, 1.0, v34
	v_rcp_f32_e32 v40, v34
	v_mul_f32_e32 v34, 0xbfb8aa3b, v39
	v_exp_f32_e32 v34, v34
	s_nop 0
	v_add_f32_e32 v34, 1.0, v34
	v_rcp_f32_e32 v41, v34
	s_nop 0
	v_pk_mul_f32 v[38:39], v[40:41], v[38:39]
	v_lshlrev_b32_e32 v40, 16, v3
	v_and_b32_e32 v41, 0xffff0000, v3
	v_pk_fma_f32 v[40:41], v[6:7], v[42:43], v[40:41] neg_lo:[1,0,0] neg_hi:[1,0,0]
	v_lshlrev_b32_e32 v42, 16, v33
	v_mul_f32_e32 v3, 0xbfb8aa3b, v42
	v_exp_f32_e32 v3, v3
	v_and_b32_e32 v43, 0xffff0000, v33
	v_mov_b32_e32 v29, v40
	v_add_f32_e32 v3, 1.0, v3
	v_rcp_f32_e32 v44, v3
	v_mul_f32_e32 v3, 0xbfb8aa3b, v43
	v_exp_f32_e32 v3, v3
	s_nop 0
	v_add_f32_e32 v3, 1.0, v3
	v_rcp_f32_e32 v45, v3
	v_and_b32_e32 v3, 0xffff0000, v28
	v_pk_mul_f32 v[42:43], v[44:45], v[42:43]
	v_lshlrev_b32_e32 v44, 16, v2
	v_and_b32_e32 v45, 0xffff0000, v2
	v_lshlrev_b32_e32 v2, 16, v28
	v_pk_fma_f32 v[2:3], v[6:7], v[2:3], v[44:45] neg_lo:[1,0,0] neg_hi:[1,0,0]
	v_mov_b32_e32 v45, v41
	v_mov_b32_e32 v28, v2
	v_pk_mul_f32 v[28:29], v[28:29], v[28:29]
	v_mov_b32_e32 v44, v3
	v_pk_fma_f32 v[28:29], v[44:45], v[44:45], v[28:29]
	v_lshlrev_b32_e32 v44, 16, v32
	v_add_f32_e32 v28, v28, v29
	v_add_f32_e32 v28, v31, v28
	v_add_f32_e32 v28, v30, v28
	v_and_b32_e32 v45, 0xffff0000, v32
	v_mul_f32_e32 v32, 0xbfb8aa3b, v44
	v_add_f32_dpp v28, v28, v28 quad_perm:[1,0,3,2] row_mask:0xf bank_mask:0xf bound_ctrl:1
	v_mul_f32_e32 v33, 0xbfb8aa3b, v45
	v_exp_f32_e32 v32, v32
	v_add_f32_dpp v28, v28, v28 quad_perm:[2,3,0,1] row_mask:0xf bank_mask:0xf bound_ctrl:1
	v_exp_f32_e32 v33, v33
	v_add_f32_e32 v32, 1.0, v32
	v_add_f32_dpp v28, v28, v28 row_half_mirror row_mask:0xf bank_mask:0xf bound_ctrl:1
	v_add_f32_e32 v33, 1.0, v33
	v_rcp_f32_e32 v32, v32
	v_add_f32_dpp v28, v28, v28 row_mirror row_mask:0xf bank_mask:0xf bound_ctrl:1
	v_fmamk_f32 v28, v28, 0x3c000000, v245
	v_cmp_gt_f32_e32 vcc, s75, v28
	v_mul_f32_e32 v29, 0x4b800000, v28
	v_rcp_f32_e32 v33, v33
	v_cndmask_b32_e32 v28, v28, v29, vcc
	v_rsq_f32_e32 v28, v28
	v_pk_mul_f32 v[32:33], v[32:33], v[44:45]
	v_mul_f32_e32 v29, 0x45800000, v28
	v_cndmask_b32_e32 v28, v28, v29, vcc
	v_pk_mul_f32 v[2:3], v[2:3], v[28:29] op_sel_hi:[1,0]
	v_pk_mul_f32 v[30:31], v[40:41], v[28:29] op_sel_hi:[1,0]
	v_pk_mul_f32 v[2:3], v[8:9], v[2:3]
	v_pk_mul_f32 v[30:31], v[10:11], v[30:31]
	v_pk_mul_f32 v[4:5], v[4:5], v[28:29] op_sel_hi:[1,0]
	v_pk_mul_f32 v[2:3], v[32:33], v[2:3]
	v_pk_mul_f32 v[30:31], v[42:43], v[30:31]
	v_pk_mul_f32 v[4:5], v[12:13], v[4:5]
	v_cvt_pk_bf16_f32 v2, v2, v3
	v_cvt_pk_bf16_f32 v3, v30, v31
	v_pk_mul_f32 v[4:5], v[38:39], v[4:5]
	v_lshlrev_b32_e32 v30, 16, v35
	v_cvt_pk_bf16_f32 v4, v4, v5
	v_mul_f32_e32 v5, 0xbfb8aa3b, v30
	v_exp_f32_e32 v5, v5
	v_and_b32_e32 v31, 0xffff0000, v35
	v_pk_mul_f32 v[28:29], v[36:37], v[28:29] op_sel_hi:[1,0]
	v_add_f32_e32 v5, 1.0, v5
	v_rcp_f32_e32 v32, v5
	v_mul_f32_e32 v5, 0xbfb8aa3b, v31
	v_exp_f32_e32 v5, v5
	v_pk_mul_f32 v[28:29], v[14:15], v[28:29]
	v_add_f32_e32 v5, 1.0, v5
	v_rcp_f32_e32 v33, v5
	s_nop 0
	v_pk_mul_f32 v[30:31], v[32:33], v[30:31]
	s_nop 0
	v_pk_mul_f32 v[28:29], v[30:31], v[28:29]
	s_nop 0
	v_cvt_pk_bf16_f32 v5, v28, v29
	v_lshl_add_u64 v[28:29], v[20:21], 0, v[0:1]
	v_lshl_add_u64 v[20:21], v[20:21], 0, s[42:43]
	global_store_dwordx4 v[28:29], v[2:5], off
	s_cbranch_scc1 .LBB0_709
	s_branch .LBB0_632
